# v25 + S5 pass-1 tile loop: the LDS-DMA loads of the never-read B-high buffers removed (6 -> 4 loads in the heavy phases), counted waits vmcnt(8) -> vmcnt(6)
# speedup vs baseline: 1.0095x; 1.0095x over previous
; #define PG8_STAGE(bufoff, gbase, voff) do { _Pragma("unroll") for (int _i = 0; _i < 2; ++_i) \
;         __builtin_amdgcn_global_load_lds((const unsigned*)((const char*)(gbase) + (voff)[_i]), (PG8_LAS unsigned*)(lds + (bufoff) + ldsw + _i * 8192), 16, 0, 0); } while (0)
; #define PG8_LDA(dst, b, h) do { _Pragma("unroll") for (int m = 0; m < 4; ++m) _Pragma("unroll") for (int k = 0; k < 2; ++k) dst[m][k] = *(const PG8_LAS bf16x8*)(lds + PG8_SA(b, h) + aoff + m * 2048 + k * 1024); } while (0)
; #define PG8_LDB(dst, b, h) do { _Pragma("unroll") for (int n = 0; n < 2; ++n) _Pragma("unroll") for (int k = 0; k < 2; ++k) dst[n][k] = *(const PG8_LAS bf16x8*)(lds + PG8_SB(b, h) + boff + n * 2048 + k * 1024); } while (0)
; #define PG8_MMA(ai, bj, At, Bt) do { __builtin_amdgcn_s_setprio(1); _Pragma("unroll") for (int m = 0; m < 4; ++m) _Pragma("unroll") for (int n = 0; n < 2; ++n) _Pragma("unroll") for (int k = 0; k < 2; ++k) \
;         acc[ai][bj][m][n] = __builtin_amdgcn_mfma_f32_16x16x32_bf16(Bt[n][k], At[m][k], acc[ai][bj][m][n], 0, 0, 0); __builtin_amdgcn_s_setprio(0); } while (0)
; #define PG8_WAIT_V(n) asm volatile("s_waitcnt vmcnt(" #n ")" ::: "memory")
; #define PG8_WAIT_L(n) asm volatile("s_waitcnt lgkmcnt(" #n ")" ::: "memory")
; #define PG8_BAR __builtin_amdgcn_s_barrier()
; #define PG8_SCHED __builtin_amdgcn_sched_barrier(0)
; template <class Epi, class Sched, bool ALIGN_EPI = false, bool SP2 = false>
; __device__ __forceinline__ void gemm_phase(PG8_LAS unsigned char* lds, const Gemm g, const Sched& S, const Epi& E, const int tid) {
;     ...
;             PG8_LDB(B0, 0, 0); PG8_LDB(B1, 0, 1); PG8_SCHED; PG8_LDA(At, 0, 0); PG8_STAGE(PG8_SA(1, 1), a1 + hstepA, voffA);
;             PG8_WAIT_V(8); PG8_WAIT_L(0); PG8_BAR; PG8_MMA(0, 0, At, B0); PG8_MMA(0, 1, At, B1); PG8_BAR; PG8_SCHED;
;             PG8_LDA(At, 0, 1); PG8_STAGE(PG8_SB(0, 0), b2, voffB); PG8_STAGE(PG8_SB(0, 1), b2 + hstepB, voffB); PG8_STAGE(PG8_SA(0, 0), a2, voffA);
;             PG8_WAIT_V(8); PG8_WAIT_L(0); PG8_BAR; PG8_MMA(1, 0, At, B0); PG8_MMA(1, 1, At, B1); PG8_BAR; PG8_SCHED;
;             PG8_LDB(B0, 1, 0); PG8_LDB(B1, 1, 1); PG8_SCHED; PG8_LDA(At, 1, 0); PG8_STAGE(PG8_SA(0, 1), a2 + hstepA, voffA);
;             PG8_WAIT_V(8); PG8_WAIT_L(0); PG8_BAR; PG8_MMA(0, 0, At, B0); PG8_MMA(0, 1, At, B1); PG8_BAR; PG8_SCHED;
.LBB0_282:
	s_add_i32 s60, 0, 0x10000
	v_add_u32_e32 v132, s60, v72
	ds_read_b128 v[0:3], v132
	ds_read_b128 v[4:7], v132 offset:1024
	ds_read_b128 v[8:11], v132 offset:2048
	ds_read_b128 v[12:15], v132 offset:3072
	s_add_u32 s58, s24, 0x18080
	s_addc_u32 s59, s25, 0
	s_add_i32 s61, s36, 0xc000
	v_lshl_add_u64 v[48:49], s[58:59], 0, v[68:69]
	s_mov_b32 m0, s61
	s_add_i32 s21, s36, 0xe000
	ds_read_b128 v[16:19], v73
	ds_read_b128 v[20:23], v73 offset:1024
	ds_read_b128 v[24:27], v73 offset:2048
	ds_read_b128 v[28:31], v73 offset:3072
	ds_read_b128 v[32:35], v73 offset:4096
	ds_read_b128 v[36:39], v73 offset:5120
	ds_read_b128 v[40:43], v73 offset:6144
	ds_read_b128 v[44:47], v73 offset:7168
	global_load_lds_dwordx4 v[48:49], off
	v_lshl_add_u64 v[48:49], s[58:59], 0, v[66:67]
	s_mov_b32 m0, s21
	s_nop 0
	global_load_lds_dwordx4 v[48:49], off
	s_waitcnt vmcnt(6)
	s_waitcnt lgkmcnt(0)
	s_barrier
	s_setprio 1
	s_waitcnt lgkmcnt(0)
	v_mfma_f32_16x16x32_bf16 v[48:51], v[0:3], v[16:19], 0
	v_mfma_f32_16x16x32_bf16 v[16:19], v[8:11], v[16:19], 0
	v_mfma_f32_16x16x32_bf16 v[48:51], v[4:7], v[20:23], v[48:51]
	v_mfma_f32_16x16x32_bf16 v[16:19], v[12:15], v[20:23], v[16:19]
	v_mfma_f32_16x16x32_bf16 v[20:23], v[0:3], v[24:27], 0
	v_mfma_f32_16x16x32_bf16 v[24:27], v[8:11], v[24:27], 0
	v_mfma_f32_16x16x32_bf16 v[20:23], v[4:7], v[28:31], v[20:23]
	v_mfma_f32_16x16x32_bf16 v[24:27], v[12:15], v[28:31], v[24:27]
	v_mfma_f32_16x16x32_bf16 v[28:31], v[0:3], v[32:35], 0
	v_mfma_f32_16x16x32_bf16 v[32:35], v[8:11], v[32:35], 0
	v_mfma_f32_16x16x32_bf16 v[28:31], v[4:7], v[36:39], v[28:31]
	v_mfma_f32_16x16x32_bf16 v[32:35], v[12:15], v[36:39], v[32:35]
	v_mfma_f32_16x16x32_bf16 v[36:39], v[0:3], v[40:43], 0
	v_mfma_f32_16x16x32_bf16 v[40:43], v[8:11], v[40:43], 0
	v_mfma_f32_16x16x32_bf16 v[36:39], v[4:7], v[44:47], v[36:39]
	v_mfma_f32_16x16x32_bf16 v[40:43], v[12:15], v[44:47], v[40:43]
	s_setprio 0
	s_setprio 1
	s_setprio 0
	s_barrier
	s_add_i32 s60, s60, s35
	v_lshl_add_u64 v[122:123], s[26:27], 0, v[204:205]
	s_add_i32 s58, s60, 0x2000
	v_lshl_add_u64 v[90:91], v[122:123], 0, s[84:85]
	s_mov_b32 m0, s60
	v_lshl_add_u64 v[124:125], s[26:27], 0, v[64:65]
	s_add_u32 s62, s26, 0x10100
	ds_read_b128 v[44:47], v73 offset:16384
	ds_read_b128 v[52:55], v73 offset:17408
	ds_read_b128 v[56:59], v73 offset:18432
	ds_read_b128 v[60:63], v73 offset:19456
	ds_read_b128 v[74:77], v73 offset:20480
	ds_read_b128 v[78:81], v73 offset:21504
	ds_read_b128 v[82:85], v73 offset:22528
	ds_read_b128 v[86:89], v73 offset:23552
	global_load_lds_dwordx4 v[90:91], off
	v_lshl_add_u64 v[90:91], v[124:125], 0, s[84:85]
	s_mov_b32 m0, s58
	s_addc_u32 s63, s27, 0
	global_load_lds_dwordx4 v[90:91], off
	v_lshl_add_u64 v[90:91], s[62:63], 0, v[204:205]
	s_mov_b32 m0, s37
	v_lshl_add_u64 v[126:127], s[24:25], 0, v[68:69]
	v_lshl_add_u64 v[90:91], s[62:63], 0, v[64:65]
	s_mov_b32 m0, s42
	v_lshl_add_u64 v[128:129], s[24:25], 0, v[66:67]
	v_lshl_add_u64 v[90:91], v[126:127], 0, s[84:85]
	s_mov_b32 m0, s36
	s_nop 0
	global_load_lds_dwordx4 v[90:91], off
	v_lshl_add_u64 v[90:91], v[128:129], 0, s[84:85]
	s_mov_b32 m0, s43
	s_nop 0
	global_load_lds_dwordx4 v[90:91], off
	s_waitcnt vmcnt(6)
	s_waitcnt lgkmcnt(0)
	s_barrier
	s_setprio 1
	s_waitcnt lgkmcnt(0)
	v_mfma_f32_16x16x32_bf16 v[90:93], v[0:3], v[44:47], 0
	v_mfma_f32_16x16x32_bf16 v[44:47], v[8:11], v[44:47], 0
	v_mfma_f32_16x16x32_bf16 v[90:93], v[4:7], v[52:55], v[90:93]
	v_mfma_f32_16x16x32_bf16 v[44:47], v[12:15], v[52:55], v[44:47]
	v_mfma_f32_16x16x32_bf16 v[52:55], v[0:3], v[56:59], 0
	v_mfma_f32_16x16x32_bf16 v[56:59], v[8:11], v[56:59], 0
	v_mfma_f32_16x16x32_bf16 v[52:55], v[4:7], v[60:63], v[52:55]
	v_mfma_f32_16x16x32_bf16 v[56:59], v[12:15], v[60:63], v[56:59]
	v_mfma_f32_16x16x32_bf16 v[60:63], v[0:3], v[74:77], 0
	v_mfma_f32_16x16x32_bf16 v[0:3], v[0:3], v[82:85], 0
	v_mfma_f32_16x16x32_bf16 v[60:63], v[4:7], v[78:81], v[60:63]
	v_mfma_f32_16x16x32_bf16 v[0:3], v[4:7], v[86:89], v[0:3]
	v_mfma_f32_16x16x32_bf16 v[4:7], v[8:11], v[82:85], 0
	v_mfma_f32_16x16x32_bf16 v[74:77], v[8:11], v[74:77], 0
	v_mfma_f32_16x16x32_bf16 v[4:7], v[12:15], v[86:89], v[4:7]
	v_mfma_f32_16x16x32_bf16 v[74:77], v[12:15], v[78:81], v[74:77]
	s_setprio 0
	s_setprio 1
	s_setprio 0
	s_barrier
	s_add_i32 s59, 0, 0x18000
	v_add_u32_e32 v133, s59, v72
	ds_read_b128 v[8:11], v133
	ds_read_b128 v[12:15], v133 offset:1024
	ds_read_b128 v[78:81], v133 offset:2048
	ds_read_b128 v[82:85], v133 offset:3072
	s_add_u32 s62, s24, 0x18100
	s_addc_u32 s63, s25, 0
	s_mov_b32 m0, s46
	v_lshl_add_u64 v[130:131], s[62:63], 0, v[68:69]
	ds_read_b128 v[86:89], v73 offset:32768
	ds_read_b128 v[94:97], v73 offset:33792
	ds_read_b128 v[98:101], v73 offset:34816
	ds_read_b128 v[102:105], v73 offset:35840
	ds_read_b128 v[106:109], v73 offset:36864
	ds_read_b128 v[110:113], v73 offset:37888
	ds_read_b128 v[114:117], v73 offset:38912
	ds_read_b128 v[118:121], v73 offset:39936
	global_load_lds_dwordx4 v[130:131], off
	v_lshl_add_u64 v[130:131], s[62:63], 0, v[66:67]
	s_mov_b32 m0, s47
	s_nop 0
	global_load_lds_dwordx4 v[130:131], off
	s_waitcnt vmcnt(6)
	s_waitcnt lgkmcnt(0)
	s_barrier
; #define PG8_STAGE(bufoff, gbase, voff) do { _Pragma("unroll") for (int _i = 0; _i < 2; ++_i) \
;         __builtin_amdgcn_global_load_lds((const unsigned*)((const char*)(gbase) + (voff)[_i]), (PG8_LAS unsigned*)(lds + (bufoff) + ldsw + _i * 8192), 16, 0, 0); } while (0)
; #define PG8_LDA(dst, b, h) do { _Pragma("unroll") for (int m = 0; m < 4; ++m) _Pragma("unroll") for (int k = 0; k < 2; ++k) dst[m][k] = *(const PG8_LAS bf16x8*)(lds + PG8_SA(b, h) + aoff + m * 2048 + k * 1024); } while (0)
; #define PG8_LDB(dst, b, h) do { _Pragma("unroll") for (int n = 0; n < 2; ++n) _Pragma("unroll") for (int k = 0; k < 2; ++k) dst[n][k] = *(const PG8_LAS bf16x8*)(lds + PG8_SB(b, h) + boff + n * 2048 + k * 1024); } while (0)
; #define PG8_MMA(ai, bj, At, Bt) do { __builtin_amdgcn_s_setprio(1); _Pragma("unroll") for (int m = 0; m < 4; ++m) _Pragma("unroll") for (int n = 0; n < 2; ++n) _Pragma("unroll") for (int k = 0; k < 2; ++k) \
;         acc[ai][bj][m][n] = __builtin_amdgcn_mfma_f32_16x16x32_bf16(Bt[n][k], At[m][k], acc[ai][bj][m][n], 0, 0, 0); __builtin_amdgcn_s_setprio(0); } while (0)
; #define PG8_BAR __builtin_amdgcn_s_barrier()
; template <class Epi, class Sched, bool ALIGN_EPI = false, bool SP2 = false>
; __device__ __forceinline__ void gemm_phase(PG8_LAS unsigned char* lds, const Gemm g, const Sched& S, const Epi& E, const int tid) {
;     ...
;             PG8_LDB(B0, 0, 0); PG8_LDB(B1, 0, 1); PG8_SCHED; PG8_LDA(At, 0, 0); PG8_STAGE(PG8_SA(1, 1), a1 + hstepA, voffA);
;             PG8_WAIT_V(8); PG8_WAIT_L(0); PG8_BAR; PG8_MMA(0, 0, At, B0); PG8_MMA(0, 1, At, B1); PG8_BAR; PG8_SCHED;
;             PG8_LDA(At, 0, 1); PG8_STAGE(PG8_SB(0, 0), b2, voffB); PG8_STAGE(PG8_SB(0, 1), b2 + hstepB, voffB); PG8_STAGE(PG8_SA(0, 0), a2, voffA);
;             PG8_WAIT_V(8); PG8_WAIT_L(0); PG8_BAR; PG8_MMA(1, 0, At, B0); PG8_MMA(1, 1, At, B1); PG8_BAR; PG8_SCHED;
;             PG8_LDB(B0, 1, 0); PG8_LDB(B1, 1, 1); PG8_SCHED; PG8_LDA(At, 1, 0); PG8_STAGE(PG8_SA(0, 1), a2 + hstepA, voffA);
;             PG8_WAIT_V(8); PG8_WAIT_L(0); PG8_BAR; PG8_MMA(0, 0, At, B0); PG8_MMA(0, 1, At, B1); PG8_BAR; PG8_SCHED;
;             PG8_LDA(At, 1, 1); PG8_STAGE(PG8_SB(1, 0), b3, voffB); PG8_STAGE(PG8_SB(1, 1), b3 + hstepB, voffB); PG8_STAGE(PG8_SA(1, 0), a3, voffA);
;             PG8_WAIT_V(8); PG8_WAIT_L(0); PG8_BAR; PG8_MMA(1, 0, At, B0); PG8_MMA(1, 1, At, B1); PG8_BAR; PG8_SCHED;
	s_setprio 1
	s_waitcnt lgkmcnt(0)
	v_mfma_f32_16x16x32_bf16 v[48:51], v[8:11], v[86:89], v[48:51]
	v_mfma_f32_16x16x32_bf16 v[16:19], v[78:81], v[86:89], v[16:19]
	v_mfma_f32_16x16x32_bf16 v[20:23], v[8:11], v[98:101], v[20:23]
	v_mfma_f32_16x16x32_bf16 v[24:27], v[78:81], v[98:101], v[24:27]
	v_mfma_f32_16x16x32_bf16 v[28:31], v[8:11], v[106:109], v[28:31]
	v_mfma_f32_16x16x32_bf16 v[32:35], v[78:81], v[106:109], v[32:35]
	v_mfma_f32_16x16x32_bf16 v[36:39], v[8:11], v[114:117], v[36:39]
	v_mfma_f32_16x16x32_bf16 v[40:43], v[78:81], v[114:117], v[40:43]
	v_mfma_f32_16x16x32_bf16 v[48:51], v[12:15], v[94:97], v[48:51]
	v_mfma_f32_16x16x32_bf16 v[16:19], v[82:85], v[94:97], v[16:19]
	v_mfma_f32_16x16x32_bf16 v[20:23], v[12:15], v[102:105], v[20:23]
	v_mfma_f32_16x16x32_bf16 v[24:27], v[82:85], v[102:105], v[24:27]
	v_mfma_f32_16x16x32_bf16 v[28:31], v[12:15], v[110:113], v[28:31]
	v_mfma_f32_16x16x32_bf16 v[32:35], v[82:85], v[110:113], v[32:35]
	v_mfma_f32_16x16x32_bf16 v[36:39], v[12:15], v[118:121], v[36:39]
	v_mfma_f32_16x16x32_bf16 v[40:43], v[82:85], v[118:121], v[40:43]
	s_setprio 0
	s_setprio 1
	s_setprio 0
	s_barrier
	s_add_i32 s62, s59, s35
	s_add_i32 s59, s62, 0x2000
	v_lshl_add_u64 v[122:123], v[122:123], 0, s[94:95]
	s_mov_b32 m0, s62
	s_add_u32 s26, s26, 0x10180
	ds_read_b128 v[86:89], v73 offset:49152
	ds_read_b128 v[94:97], v73 offset:50176
	ds_read_b128 v[98:101], v73 offset:51200
	ds_read_b128 v[102:105], v73 offset:52224
	ds_read_b128 v[106:109], v73 offset:53248
	ds_read_b128 v[110:113], v73 offset:54272
	ds_read_b128 v[114:117], v73 offset:55296
	ds_read_b128 v[118:121], v73 offset:56320
	global_load_lds_dwordx4 v[122:123], off
	v_lshl_add_u64 v[122:123], v[124:125], 0, s[94:95]
	s_mov_b32 m0, s59
	s_addc_u32 s27, s27, 0
	global_load_lds_dwordx4 v[122:123], off
	v_lshl_add_u64 v[122:123], s[26:27], 0, v[204:205]
	s_mov_b32 m0, s54
	s_nop 0
	v_lshl_add_u64 v[122:123], s[26:27], 0, v[64:65]
	s_mov_b32 m0, s55
	s_nop 0
	v_lshl_add_u64 v[122:123], v[126:127], 0, s[94:95]
	s_mov_b32 m0, s49
	s_nop 0
	global_load_lds_dwordx4 v[122:123], off
	v_lshl_add_u64 v[122:123], v[128:129], 0, s[94:95]
	s_mov_b32 m0, s50
	s_nop 0
	global_load_lds_dwordx4 v[122:123], off
	s_waitcnt vmcnt(6)
	s_waitcnt lgkmcnt(0)
	s_barrier
	s_setprio 1
	s_waitcnt lgkmcnt(0)
	v_mfma_f32_16x16x32_bf16 v[44:47], v[78:81], v[86:89], v[44:47]
	v_mfma_f32_16x16x32_bf16 v[52:55], v[8:11], v[98:101], v[52:55]
	v_mfma_f32_16x16x32_bf16 v[56:59], v[78:81], v[98:101], v[56:59]
	v_mfma_f32_16x16x32_bf16 v[60:63], v[8:11], v[106:109], v[60:63]
	v_mfma_f32_16x16x32_bf16 v[0:3], v[8:11], v[114:117], v[0:3]
	v_mfma_f32_16x16x32_bf16 v[4:7], v[78:81], v[114:117], v[4:7]
	v_mfma_f32_16x16x32_bf16 v[90:93], v[8:11], v[86:89], v[90:93]
	v_mfma_f32_16x16x32_bf16 v[44:47], v[82:85], v[94:97], v[44:47]
	v_mfma_f32_16x16x32_bf16 v[52:55], v[12:15], v[102:105], v[52:55]
	v_mfma_f32_16x16x32_bf16 v[56:59], v[82:85], v[102:105], v[56:59]
	v_mfma_f32_16x16x32_bf16 v[60:63], v[12:15], v[110:113], v[60:63]
	v_mfma_f32_16x16x32_bf16 v[74:77], v[78:81], v[106:109], v[74:77]
	v_mfma_f32_16x16x32_bf16 v[0:3], v[12:15], v[118:121], v[0:3]
	v_mfma_f32_16x16x32_bf16 v[4:7], v[82:85], v[118:121], v[4:7]
	v_mfma_f32_16x16x32_bf16 v[90:93], v[12:15], v[94:97], v[90:93]
	v_mfma_f32_16x16x32_bf16 v[74:77], v[82:85], v[110:113], v[74:77]
	s_setprio 0
	s_setprio 1
	s_setprio 0
	s_barrier
	ds_read_b128 v[8:11], v132
	ds_read_b128 v[12:15], v132 offset:1024
	ds_read_b128 v[78:81], v132 offset:2048
	ds_read_b128 v[82:85], v132 offset:3072
	s_add_u32 s24, s24, 0x18180
	s_addc_u32 s25, s25, 0
	s_mov_b32 m0, s61
	v_lshl_add_u64 v[122:123], s[24:25], 0, v[68:69]
	ds_read_b128 v[86:89], v73
	ds_read_b128 v[94:97], v73 offset:1024
	ds_read_b128 v[98:101], v73 offset:2048
	ds_read_b128 v[102:105], v73 offset:3072
	ds_read_b128 v[106:109], v73 offset:4096
	ds_read_b128 v[110:113], v73 offset:5120
	ds_read_b128 v[114:117], v73 offset:6144
	ds_read_b128 v[118:121], v73 offset:7168
	global_load_lds_dwordx4 v[122:123], off
	v_lshl_add_u64 v[122:123], s[24:25], 0, v[66:67]
	s_mov_b32 m0, s21
	s_nop 0
	global_load_lds_dwordx4 v[122:123], off
	s_waitcnt vmcnt(6)
	s_waitcnt lgkmcnt(0)
	s_barrier
	s_setprio 1
	s_waitcnt lgkmcnt(0)
	v_mfma_f32_16x16x32_bf16 v[28:31], v[8:11], v[106:109], v[28:31]
	v_mfma_f32_16x16x32_bf16 v[48:51], v[8:11], v[86:89], v[48:51]
	v_mfma_f32_16x16x32_bf16 v[16:19], v[78:81], v[86:89], v[16:19]
	v_mfma_f32_16x16x32_bf16 v[86:89], v[12:15], v[110:113], v[28:31]
	v_mfma_f32_16x16x32_bf16 v[28:31], v[78:81], v[106:109], v[32:35]
	v_mfma_f32_16x16x32_bf16 v[32:35], v[82:85], v[110:113], v[28:31]
	v_mfma_f32_16x16x32_bf16 v[28:31], v[8:11], v[114:117], v[36:39]
	v_mfma_f32_16x16x32_bf16 v[48:51], v[12:15], v[94:97], v[48:51]
	v_mfma_f32_16x16x32_bf16 v[16:19], v[82:85], v[94:97], v[16:19]
	v_mfma_f32_16x16x32_bf16 v[20:23], v[8:11], v[98:101], v[20:23]
	v_mfma_f32_16x16x32_bf16 v[24:27], v[78:81], v[98:101], v[24:27]
	v_mfma_f32_16x16x32_bf16 v[94:97], v[12:15], v[118:121], v[28:31]
	v_mfma_f32_16x16x32_bf16 v[28:31], v[78:81], v[114:117], v[40:43]
	v_mfma_f32_16x16x32_bf16 v[20:23], v[12:15], v[102:105], v[20:23]
	v_mfma_f32_16x16x32_bf16 v[24:27], v[82:85], v[102:105], v[24:27]
	v_mfma_f32_16x16x32_bf16 v[40:43], v[82:85], v[118:121], v[28:31]
	s_setprio 0
	s_setprio 1
	s_setprio 0
	s_barrier
; #define PG8_STAGE(bufoff, gbase, voff) do { _Pragma("unroll") for (int _i = 0; _i < 2; ++_i) \
;         __builtin_amdgcn_global_load_lds((const unsigned*)((const char*)(gbase) + (voff)[_i]), (PG8_LAS unsigned*)(lds + (bufoff) + ldsw + _i * 8192), 16, 0, 0); } while (0)
; #define PG8_LDA(dst, b, h) do { _Pragma("unroll") for (int m = 0; m < 4; ++m) _Pragma("unroll") for (int k = 0; k < 2; ++k) dst[m][k] = *(const PG8_LAS bf16x8*)(lds + PG8_SA(b, h) + aoff + m * 2048 + k * 1024); } while (0)
; #define PG8_LDB(dst, b, h) do { _Pragma("unroll") for (int n = 0; n < 2; ++n) _Pragma("unroll") for (int k = 0; k < 2; ++k) dst[n][k] = *(const PG8_LAS bf16x8*)(lds + PG8_SB(b, h) + boff + n * 2048 + k * 1024); } while (0)
; #define PG8_MMA(ai, bj, At, Bt) do { __builtin_amdgcn_s_setprio(1); _Pragma("unroll") for (int m = 0; m < 4; ++m) _Pragma("unroll") for (int n = 0; n < 2; ++n) _Pragma("unroll") for (int k = 0; k < 2; ++k) \
;         acc[ai][bj][m][n] = __builtin_amdgcn_mfma_f32_16x16x32_bf16(Bt[n][k], At[m][k], acc[ai][bj][m][n], 0, 0, 0); __builtin_amdgcn_s_setprio(0); } while (0)
; #define PG8_WAIT_V(n) asm volatile("s_waitcnt vmcnt(" #n ")" ::: "memory")
; #define PG8_WAIT_L(n) asm volatile("s_waitcnt lgkmcnt(" #n ")" ::: "memory")
; #define PG8_BAR __builtin_amdgcn_s_barrier()
; template <class Epi, class Sched, bool ALIGN_EPI = false, bool SP2 = false>
; __device__ __forceinline__ void gemm_phase(PG8_LAS unsigned char* lds, const Gemm g, const Sched& S, const Epi& E, const int tid) {
;     ...
;             PG8_LDA(At, 0, 1); PG8_STAGE(PG8_SB(0, 0), b2, voffB); PG8_STAGE(PG8_SB(0, 1), b2 + hstepB, voffB); PG8_STAGE(PG8_SA(0, 0), a2, voffA);
;             PG8_WAIT_V(8); PG8_WAIT_L(0); PG8_BAR; PG8_MMA(1, 0, At, B0); PG8_MMA(1, 1, At, B1); PG8_BAR; PG8_SCHED;
;             PG8_LDB(B0, 1, 0); PG8_LDB(B1, 1, 1); PG8_SCHED; PG8_LDA(At, 1, 0); PG8_STAGE(PG8_SA(0, 1), a2 + hstepA, voffA);
;             PG8_WAIT_V(8); PG8_WAIT_L(0); PG8_BAR; PG8_MMA(0, 0, At, B0); PG8_MMA(0, 1, At, B1); PG8_BAR; PG8_SCHED;
;             PG8_LDA(At, 1, 1); PG8_STAGE(PG8_SB(1, 0), b3, voffB); PG8_STAGE(PG8_SB(1, 1), b3 + hstepB, voffB); PG8_STAGE(PG8_SA(1, 0), a3, voffA);
;             PG8_WAIT_V(8); PG8_WAIT_L(0); PG8_BAR; PG8_MMA(1, 0, At, B0); PG8_MMA(1, 1, At, B1); PG8_BAR; PG8_SCHED;
;     ...
;         if constexpr (ALIGN_EPI) { if (wr == 0) PG8_BAR; }
	s_mov_b32 m0, s60
	v_lshl_add_u64 v[134:135], s[22:23], 0, v[204:205]
	s_add_u32 s24, s22, 0x10000
	ds_read_b128 v[28:31], v73 offset:16384
	ds_read_b128 v[36:39], v73 offset:17408
	ds_read_b128 v[98:101], v73 offset:18432
	ds_read_b128 v[102:105], v73 offset:19456
	ds_read_b128 v[106:109], v73 offset:20480
	ds_read_b128 v[110:113], v73 offset:21504
	ds_read_b128 v[114:117], v73 offset:22528
	ds_read_b128 v[118:121], v73 offset:23552
	global_load_lds_dwordx4 v[134:135], off
	v_lshl_add_u64 v[136:137], s[22:23], 0, v[64:65]
	s_mov_b32 m0, s58
	s_addc_u32 s25, s23, 0
	global_load_lds_dwordx4 v[136:137], off
	v_lshl_add_u64 v[122:123], s[24:25], 0, v[204:205]
	s_mov_b32 m0, s37
	v_lshl_add_u64 v[138:139], s[0:1], 0, v[68:69]
	v_lshl_add_u64 v[122:123], s[24:25], 0, v[64:65]
	s_mov_b32 m0, s42
	v_lshl_add_u64 v[140:141], s[0:1], 0, v[66:67]
	s_mov_b32 m0, s36
	s_nop 0
	global_load_lds_dwordx4 v[138:139], off
	s_mov_b32 m0, s43
	s_nop 0
	global_load_lds_dwordx4 v[140:141], off
	s_waitcnt vmcnt(6)
	s_waitcnt lgkmcnt(0)
	s_barrier
	s_setprio 1
	s_waitcnt lgkmcnt(0)
	v_mfma_f32_16x16x32_bf16 v[90:93], v[8:11], v[28:31], v[90:93]
	v_mfma_f32_16x16x32_bf16 v[28:31], v[78:81], v[28:31], v[44:47]
	v_mfma_f32_16x16x32_bf16 v[44:47], v[82:85], v[36:39], v[28:31]
	v_mfma_f32_16x16x32_bf16 v[28:31], v[8:11], v[98:101], v[52:55]
	v_mfma_f32_16x16x32_bf16 v[52:55], v[12:15], v[102:105], v[28:31]
	v_mfma_f32_16x16x32_bf16 v[28:31], v[78:81], v[98:101], v[56:59]
	v_mfma_f32_16x16x32_bf16 v[98:101], v[82:85], v[102:105], v[28:31]
	v_mfma_f32_16x16x32_bf16 v[28:31], v[8:11], v[106:109], v[60:63]
	v_mfma_f32_16x16x32_bf16 v[0:3], v[8:11], v[114:117], v[0:3]
	v_mfma_f32_16x16x32_bf16 v[102:105], v[12:15], v[110:113], v[28:31]
	v_mfma_f32_16x16x32_bf16 v[28:31], v[78:81], v[106:109], v[74:77]
	v_mfma_f32_16x16x32_bf16 v[106:109], v[12:15], v[118:121], v[0:3]
	v_mfma_f32_16x16x32_bf16 v[0:3], v[78:81], v[114:117], v[4:7]
	v_mfma_f32_16x16x32_bf16 v[90:93], v[12:15], v[36:39], v[90:93]
	v_mfma_f32_16x16x32_bf16 v[74:77], v[82:85], v[110:113], v[28:31]
	v_mfma_f32_16x16x32_bf16 v[78:81], v[82:85], v[118:121], v[0:3]
	s_setprio 0
	s_setprio 1
	s_setprio 0
	s_barrier
	ds_read_b128 v[82:85], v133
	ds_read_b128 v[110:113], v133 offset:1024
	ds_read_b128 v[114:117], v133 offset:2048
	ds_read_b128 v[118:121], v133 offset:3072
	s_add_u32 s24, s0, 0x18000
	s_addc_u32 s25, s1, 0
	s_mov_b32 m0, s46
	v_lshl_add_u64 v[28:29], s[24:25], 0, v[68:69]
	ds_read_b128 v[0:3], v73 offset:32768
	ds_read_b128 v[4:7], v73 offset:33792
	ds_read_b128 v[8:11], v73 offset:34816
	ds_read_b128 v[12:15], v73 offset:35840
	ds_read_b128 v[56:59], v73 offset:36864
	ds_read_b128 v[60:63], v73 offset:37888
	ds_read_b128 v[122:125], v73 offset:38912
	ds_read_b128 v[126:129], v73 offset:39936
	global_load_lds_dwordx4 v[28:29], off
	v_lshl_add_u64 v[28:29], s[24:25], 0, v[66:67]
	s_mov_b32 m0, s47
	s_nop 0
	global_load_lds_dwordx4 v[28:29], off
	s_waitcnt vmcnt(6)
	s_waitcnt lgkmcnt(0)
	s_barrier
	s_setprio 1
	s_waitcnt lgkmcnt(0)
	v_mfma_f32_16x16x32_bf16 v[28:31], v[82:85], v[0:3], v[48:51]
	v_mfma_f32_16x16x32_bf16 v[0:3], v[114:117], v[0:3], v[16:19]
	v_mfma_f32_16x16x32_bf16 v[36:39], v[118:121], v[4:7], v[0:3]
	v_mfma_f32_16x16x32_bf16 v[0:3], v[82:85], v[8:11], v[20:23]
	v_mfma_f32_16x16x32_bf16 v[16:19], v[110:113], v[12:15], v[0:3]
	v_mfma_f32_16x16x32_bf16 v[0:3], v[114:117], v[8:11], v[24:27]
	v_mfma_f32_16x16x32_bf16 v[20:23], v[118:121], v[12:15], v[0:3]
	v_mfma_f32_16x16x32_bf16 v[0:3], v[82:85], v[56:59], v[86:89]
	v_mfma_f32_16x16x32_bf16 v[8:11], v[110:113], v[60:63], v[0:3]
	v_mfma_f32_16x16x32_bf16 v[0:3], v[114:117], v[56:59], v[32:35]
	v_mfma_f32_16x16x32_bf16 v[28:31], v[110:113], v[4:7], v[28:31]
	v_mfma_f32_16x16x32_bf16 v[12:15], v[118:121], v[60:63], v[0:3]
	v_mfma_f32_16x16x32_bf16 v[0:3], v[82:85], v[122:125], v[94:97]
	v_mfma_f32_16x16x32_bf16 v[4:7], v[114:117], v[122:125], v[40:43]
	v_mfma_f32_16x16x32_bf16 v[0:3], v[110:113], v[126:129], v[0:3]
	v_mfma_f32_16x16x32_bf16 v[4:7], v[118:121], v[126:129], v[4:7]
	s_setprio 0
	s_setprio 1
	s_setprio 0
	s_barrier
	s_mov_b32 m0, s62
	v_lshl_add_u64 v[48:49], v[134:135], 0, s[82:83]
	s_add_u32 s24, s22, 0x10080
	ds_read_b128 v[24:27], v73 offset:49152
	ds_read_b128 v[32:35], v73 offset:50176
	ds_read_b128 v[40:43], v73 offset:51200
	ds_read_b128 v[86:89], v73 offset:52224
	ds_read_b128 v[94:97], v73 offset:53248
	ds_read_b128 v[122:125], v73 offset:54272
	ds_read_b128 v[126:129], v73 offset:55296
	ds_read_b128 v[130:133], v73 offset:56320
	global_load_lds_dwordx4 v[48:49], off
	v_lshl_add_u64 v[48:49], v[136:137], 0, s[82:83]
	s_mov_b32 m0, s59
	s_addc_u32 s25, s23, 0
	global_load_lds_dwordx4 v[48:49], off
	v_lshl_add_u64 v[48:49], s[24:25], 0, v[204:205]
	s_mov_b32 m0, s54
	s_nop 0
	v_lshl_add_u64 v[48:49], s[24:25], 0, v[64:65]
	s_mov_b32 m0, s55
	s_nop 0
	v_lshl_add_u64 v[48:49], v[138:139], 0, s[82:83]
	s_mov_b32 m0, s49
	s_nop 0
	global_load_lds_dwordx4 v[48:49], off
	v_lshl_add_u64 v[48:49], v[140:141], 0, s[82:83]
	s_mov_b32 m0, s50
	s_nop 0
	global_load_lds_dwordx4 v[48:49], off
	s_waitcnt vmcnt(6)
	s_waitcnt lgkmcnt(0)
	s_barrier
	s_setprio 1
	s_waitcnt lgkmcnt(0)
	v_mfma_f32_16x16x32_bf16 v[48:51], v[82:85], v[24:27], v[90:93]
	v_mfma_f32_16x16x32_bf16 v[24:27], v[114:117], v[24:27], v[44:47]
	v_mfma_f32_16x16x32_bf16 v[60:63], v[118:121], v[32:35], v[24:27]
	v_mfma_f32_16x16x32_bf16 v[24:27], v[82:85], v[40:43], v[52:55]
	v_mfma_f32_16x16x32_bf16 v[56:59], v[110:113], v[32:35], v[48:51]
	v_mfma_f32_16x16x32_bf16 v[48:51], v[110:113], v[86:89], v[24:27]
	v_mfma_f32_16x16x32_bf16 v[24:27], v[114:117], v[40:43], v[98:101]
	v_mfma_f32_16x16x32_bf16 v[52:55], v[118:121], v[86:89], v[24:27]
	v_mfma_f32_16x16x32_bf16 v[24:27], v[82:85], v[94:97], v[102:105]
	v_mfma_f32_16x16x32_bf16 v[40:43], v[110:113], v[122:125], v[24:27]
	v_mfma_f32_16x16x32_bf16 v[24:27], v[114:117], v[94:97], v[74:77]
	v_mfma_f32_16x16x32_bf16 v[44:47], v[118:121], v[122:125], v[24:27]
	v_mfma_f32_16x16x32_bf16 v[24:27], v[82:85], v[126:129], v[106:109]
	v_mfma_f32_16x16x32_bf16 v[32:35], v[114:117], v[126:129], v[78:81]
	v_mfma_f32_16x16x32_bf16 v[24:27], v[110:113], v[130:133], v[24:27]
	v_mfma_f32_16x16x32_bf16 v[32:35], v[118:121], v[130:133], v[32:35]
	s_setprio 0
	s_setprio 1
	s_setprio 0
	s_barrier
	s_andn2_b64 vcc, exec, s[16:17]
	s_cbranch_vccnz .LBB0_284
	s_barrier
